# o19 + indexer score accumulation as two chained pk_fma (one packed op and one hazard nop less per output pair)
# baseline (speedup 1.0000x reference)
.LBB0_1414:
	ds_read_b128 v[122:125], v164
	ds_read_b128 v[114:117], v164 offset:32
	ds_read_b128 v[106:109], v164 offset:64
	ds_read_b128 v[98:101], v164 offset:96
	ds_read_b128 v[126:129], v164 offset:128
	ds_read_b128 v[118:121], v164 offset:160
	ds_read_b128 v[110:113], v164 offset:192
	ds_read_b128 v[102:105], v164 offset:224
	v_add_u32_e32 v2, s4, v134
	ds_read_b64 v[152:153], v2
	s_waitcnt vmcnt(7) lgkmcnt(8)
	v_mfma_f32_32x32x16_bf16 v[2:17], v[50:53], v[122:125], 0
	s_add_i32 s4, s4, 8
	v_add_u32_e32 v164, 0x100, v164
	s_cmp_eq_u32 s4, 64
	s_waitcnt lgkmcnt(4)
	v_mfma_f32_32x32x16_bf16 v[18:33], v[50:53], v[126:129], 0
	s_waitcnt vmcnt(6)
	v_mfma_f32_32x32x16_bf16 v[2:17], v[54:57], v[114:117], v[2:17]
	s_waitcnt lgkmcnt(3)
	v_mfma_f32_32x32x16_bf16 v[18:33], v[54:57], v[118:121], v[18:33]
	s_waitcnt vmcnt(5)
	v_mfma_f32_32x32x16_bf16 v[2:17], v[62:65], v[106:109], v[2:17]
	s_waitcnt lgkmcnt(2)
	v_mfma_f32_32x32x16_bf16 v[18:33], v[62:65], v[110:113], v[18:33]
	s_waitcnt vmcnt(4)
	v_mfma_f32_32x32x16_bf16 v[2:17], v[70:73], v[98:101], v[2:17]
	s_waitcnt lgkmcnt(1)
	v_mfma_f32_32x32x16_bf16 v[18:33], v[70:73], v[102:105], v[18:33]
	s_nop 9
	v_max_f32_e32 v166, 0, v3
	v_max_f32_e32 v2, 0, v2
	v_max_f32_e32 v167, 0, v18
	v_max_f32_e32 v3, 0, v19
	s_waitcnt lgkmcnt(0)
	v_pk_fma_f32 v[78:79], v[152:153], v[2:3], v[78:79]
	s_nop 0
	v_pk_fma_f32 v[78:79], v[152:153], v[166:167], v[78:79] op_sel:[1,1,0] op_sel_hi:[0,0,1]
	v_max_f32_e32 v19, 0, v20
	v_max_f32_e32 v18, 0, v5
	v_max_f32_e32 v2, 0, v4
	v_max_f32_e32 v3, 0, v21
	v_pk_fma_f32 v[80:81], v[152:153], v[2:3], v[80:81]
	s_nop 0
	v_pk_fma_f32 v[80:81], v[152:153], v[18:19], v[80:81] op_sel:[1,1,0] op_sel_hi:[0,0,1]
	v_max_f32_e32 v5, 0, v22
	v_max_f32_e32 v4, 0, v7
	v_max_f32_e32 v2, 0, v6
	v_max_f32_e32 v3, 0, v23
	v_pk_fma_f32 v[74:75], v[152:153], v[2:3], v[74:75]
	s_nop 0
	v_pk_fma_f32 v[74:75], v[152:153], v[4:5], v[74:75] op_sel:[1,1,0] op_sel_hi:[0,0,1]
	v_max_f32_e32 v5, 0, v24
	v_max_f32_e32 v4, 0, v9
	v_max_f32_e32 v2, 0, v8
	v_max_f32_e32 v3, 0, v25
	v_pk_fma_f32 v[76:77], v[152:153], v[2:3], v[76:77]
	s_nop 0
	v_pk_fma_f32 v[76:77], v[152:153], v[4:5], v[76:77] op_sel:[1,1,0] op_sel_hi:[0,0,1]
	v_max_f32_e32 v5, 0, v26
	v_max_f32_e32 v4, 0, v11
	v_max_f32_e32 v2, 0, v10
	v_max_f32_e32 v3, 0, v27
	v_pk_fma_f32 v[66:67], v[152:153], v[2:3], v[66:67]
	s_nop 0
	v_pk_fma_f32 v[66:67], v[152:153], v[4:5], v[66:67] op_sel:[1,1,0] op_sel_hi:[0,0,1]
	v_max_f32_e32 v5, 0, v28
	v_max_f32_e32 v4, 0, v13
	v_max_f32_e32 v2, 0, v12
	v_max_f32_e32 v3, 0, v29
	v_pk_fma_f32 v[68:69], v[152:153], v[2:3], v[68:69]
	s_nop 0
	v_pk_fma_f32 v[68:69], v[152:153], v[4:5], v[68:69] op_sel:[1,1,0] op_sel_hi:[0,0,1]
	v_max_f32_e32 v5, 0, v30
	v_max_f32_e32 v4, 0, v15
	v_max_f32_e32 v2, 0, v14
	v_max_f32_e32 v3, 0, v31
	v_pk_fma_f32 v[58:59], v[152:153], v[2:3], v[58:59]
	s_nop 0
	v_pk_fma_f32 v[58:59], v[152:153], v[4:5], v[58:59] op_sel:[1,1,0] op_sel_hi:[0,0,1]
	v_max_f32_e32 v5, 0, v32
	v_max_f32_e32 v4, 0, v17
	v_max_f32_e32 v2, 0, v16
	v_max_f32_e32 v3, 0, v33
	v_pk_mul_f32 v[4:5], v[152:153], v[4:5]
	s_waitcnt vmcnt(3)
	v_mfma_f32_32x32x16_bf16 v[18:33], v[82:85], v[122:125], 0
	v_fma_f32 v2, v152, v2, v5
	v_fma_f32 v3, v153, v3, v4
	v_add_f32_e64 v60, v60, v2
	v_add_f32_e64 v61, v61, v3
	v_mfma_f32_32x32x16_bf16 v[2:17], v[82:85], v[126:129], 0
	s_waitcnt vmcnt(2)
	v_mfma_f32_32x32x16_bf16 v[2:17], v[86:89], v[118:121], v[2:17]
	v_mfma_f32_32x32x16_bf16 v[18:33], v[86:89], v[114:117], v[18:33]
	s_waitcnt vmcnt(1)
	v_mfma_f32_32x32x16_bf16 v[2:17], v[90:93], v[110:113], v[2:17]
	v_mfma_f32_32x32x16_bf16 v[18:33], v[90:93], v[106:109], v[18:33]
	s_waitcnt vmcnt(0)
	v_mfma_f32_32x32x16_bf16 v[2:17], v[94:97], v[102:105], v[2:17]
	v_mfma_f32_32x32x16_bf16 v[18:33], v[94:97], v[98:101], v[18:33]
	s_nop 10
	v_max_f32_e32 v99, 0, v2
	v_max_f32_e32 v98, 0, v19
	v_max_f32_e32 v18, 0, v18
	v_max_f32_e32 v19, 0, v3
	v_pk_fma_f32 v[46:47], v[152:153], v[18:19], v[46:47]
	s_nop 0
	v_pk_fma_f32 v[46:47], v[152:153], v[98:99], v[46:47] op_sel:[1,1,0] op_sel_hi:[0,0,1]
	v_max_f32_e32 v19, 0, v4
	v_max_f32_e32 v18, 0, v21
	v_max_f32_e32 v2, 0, v20
	v_max_f32_e32 v3, 0, v5
	v_pk_fma_f32 v[48:49], v[152:153], v[2:3], v[48:49]
	s_nop 0
	v_pk_fma_f32 v[48:49], v[152:153], v[18:19], v[48:49] op_sel:[1,1,0] op_sel_hi:[0,0,1]
	v_max_f32_e32 v5, 0, v6
	v_max_f32_e32 v4, 0, v23
	v_max_f32_e32 v2, 0, v22
	v_max_f32_e32 v3, 0, v7
	v_pk_fma_f32 v[42:43], v[152:153], v[2:3], v[42:43]
	s_nop 0
	v_pk_fma_f32 v[42:43], v[152:153], v[4:5], v[42:43] op_sel:[1,1,0] op_sel_hi:[0,0,1]
	v_max_f32_e32 v5, 0, v8
	v_max_f32_e32 v4, 0, v25
	v_max_f32_e32 v2, 0, v24
	v_max_f32_e32 v3, 0, v9
	v_pk_fma_f32 v[44:45], v[152:153], v[2:3], v[44:45]
	s_nop 0
	v_pk_fma_f32 v[44:45], v[152:153], v[4:5], v[44:45] op_sel:[1,1,0] op_sel_hi:[0,0,1]
	v_max_f32_e32 v5, 0, v10
	v_max_f32_e32 v4, 0, v27
	v_max_f32_e32 v2, 0, v26
	v_max_f32_e32 v3, 0, v11
	v_pk_fma_f32 v[38:39], v[152:153], v[2:3], v[38:39]
	s_nop 0
	v_pk_fma_f32 v[38:39], v[152:153], v[4:5], v[38:39] op_sel:[1,1,0] op_sel_hi:[0,0,1]
	v_max_f32_e32 v5, 0, v12
	v_max_f32_e32 v4, 0, v29
	v_max_f32_e32 v2, 0, v28
	v_max_f32_e32 v3, 0, v13
	v_pk_fma_f32 v[40:41], v[152:153], v[2:3], v[40:41]
	s_nop 0
	v_pk_fma_f32 v[40:41], v[152:153], v[4:5], v[40:41] op_sel:[1,1,0] op_sel_hi:[0,0,1]
	v_max_f32_e32 v5, 0, v14
	v_max_f32_e32 v4, 0, v31
	v_max_f32_e32 v2, 0, v30
	v_max_f32_e32 v3, 0, v15
	v_pk_fma_f32 v[34:35], v[152:153], v[2:3], v[34:35]
	s_nop 0
	v_pk_fma_f32 v[34:35], v[152:153], v[4:5], v[34:35] op_sel:[1,1,0] op_sel_hi:[0,0,1]
	v_max_f32_e32 v5, 0, v16
	v_max_f32_e32 v4, 0, v33
	v_max_f32_e32 v2, 0, v32
	v_max_f32_e32 v3, 0, v17
	v_pk_fma_f32 v[36:37], v[152:153], v[2:3], v[36:37]
	s_nop 0
	v_pk_fma_f32 v[36:37], v[152:153], v[4:5], v[36:37] op_sel:[1,1,0] op_sel_hi:[0,0,1]
	s_cbranch_scc0 .LBB0_1414
	v_cmp_ge_i32_e32 vcc, s6, v162
	s_and_saveexec_b64 s[4:5], vcc
	s_cbranch_execz .LBB0_1417
	v_lshlrev_b32_e32 v2, 6, v161
	v_ashrrev_i32_e32 v3, 31, v2
	v_lshl_add_u64 v[2:3], v[2:3], 2, v[150:151]
	global_store_dwordx4 v[2:3], v[78:81], off
	global_store_dwordx4 v[2:3], v[74:77], off offset:32
	global_store_dwordx4 v[2:3], v[66:69], off offset:64
	global_store_dwordx4 v[2:3], v[58:61], off offset:96
